# tail-round half-tile split: layer-1 FFN-in GEMMs (1408 tiles = 5.5 rounds) give each last-round 256x256 tile to two WGs (rows 0-127 / 128-255), skipping the other half's MFMAs, fragment reads and stor
# baseline (speedup 1.0000x reference)
.LBB0_1557:
	s_lshl_b32 s13, s4, 5
	s_and_b32 s39, s13, 0x60
	s_lshl_b32 s12, s7, 13
	s_lshl_b32 s14, s39, 7
	s_add_u32 s4, s20, 0x8000
	s_addc_u32 s5, s21, 0
	s_add_i32 m0, s17, 0x18000
	v_lshl_add_u64 v[12:13], s[4:5], 0, v[132:133]
	s_waitcnt vmcnt(2)
	s_barrier
	global_load_lds_dwordx4 v[12:13], off
	v_lshl_add_u64 v[12:13], s[4:5], 0, v[128:129]
	s_add_i32 m0, s17, 0x1a000
	s_mov_b64 s[4:5], 0x80
	s_add_i32 s40, s17, 0x8000
	s_add_i32 s41, s17, 0xa000
	global_load_lds_dwordx4 v[12:13], off
	v_lshl_add_u64 v[0:1], v[0:1], 0, s[4:5]
	s_mov_b32 m0, s40
	s_add_u32 s10, s20, 0xc000
	global_load_lds_dwordx4 v[0:1], off
	v_lshl_add_u64 v[0:1], v[2:3], 0, s[4:5]
	s_mov_b32 m0, s41
	s_addc_u32 s11, s21, 0
	global_load_lds_dwordx4 v[0:1], off
	s_add_i32 m0, s17, 0x1c000
	v_lshl_add_u64 v[0:1], s[10:11], 0, v[132:133]
	global_load_lds_dwordx4 v[0:1], off
	v_lshl_add_u64 v[0:1], s[10:11], 0, v[128:129]
	s_add_i32 m0, s17, 0x1e000
	v_lshrrev_b32_e32 v2, 1, v6
	global_load_lds_dwordx4 v[0:1], off
	v_and_b32_e32 v2, 24, v2
	v_and_b32_e32 v1, 15, v6
	v_lshlrev_b32_e32 v3, 1, v2
	v_lshl_or_b32 v0, s7, 6, v1
	v_lshl_or_b32 v1, v1, 6, v3
	v_lshlrev_b32_e32 v3, 2, v6
	v_and_b32_e32 v3, 32, v3
	v_bitop3_b32 v6, v1, s12, v3 bitop3:0xde
	v_bitop3_b32 v164, s14, v1, v3 bitop3:0xf6
	v_and_or_b32 v1, s13, 32, v2
	v_lshlrev_b32_e32 v2, 1, v1
	v_mov_b32_e32 v3, v133
	v_lshl_add_u64 v[2:3], s[0:1], 0, v[2:3]
	s_mov_b64 s[0:1], 0x8600000
	v_lshl_add_u64 v[136:137], v[2:3], 0, s[0:1]
	v_or_b32_e32 v2, 16, v0
	v_ashrrev_i32_e32 v1, 31, v0
	v_ashrrev_i32_e32 v3, 31, v2
	v_lshlrev_b64 v[138:139], 7, v[0:1]
	v_lshlrev_b64 v[140:141], 7, v[2:3]
	v_or_b32_e32 v2, 32, v0
	v_or_b32_e32 v0, 48, v0
	v_ashrrev_i32_e32 v1, 31, v0
	v_lshlrev_b64 v[144:145], 7, v[0:1]
	v_lshlrev_b32_e32 v0, 14, v4
	v_and_b32_e32 v0, 0xffff8000, v0
	v_lshl_add_u32 v0, v5, 11, v0
	v_and_b32_e32 v1, 1, v4
	v_lshl_or_b32 v0, v1, 6, v0
	v_lshl_add_u32 v154, v7, 1, v0
	v_lshlrev_b32_e32 v0, 14, v9
	s_mov_b64 s[0:1], 0x4800
	v_and_b32_e32 v0, 0xffff8000, v0
	s_waitcnt vmcnt(6)
	s_cmpk_lt_u32 s6, 0x100
	v_lshl_add_u64 v[148:149], v[138:139], 0, s[0:1]
	s_mov_b64 s[0:1], 0x5000
	v_lshl_add_u32 v0, v8, 11, v0
	v_and_b32_e32 v1, 1, v9
	s_cselect_b64 s[6:7], -1, 0
	v_ashrrev_i32_e32 v3, 31, v2
	v_lshl_add_u64 v[150:151], v[138:139], 0, s[0:1]
	s_mov_b64 s[0:1], 0x5800
	v_lshl_or_b32 v0, v1, 6, v0
	s_add_i32 s43, 0, 0x10000
	s_add_i32 s44, 0, 0x14000
	v_lshlrev_b64 v[142:143], 7, v[2:3]
	v_lshl_add_u64 v[146:147], v[138:139], 0, s[8:9]
	v_lshl_add_u64 v[152:153], v[138:139], 0, s[0:1]
	s_ashr_i32 s42, s26, 31
	v_mov_b32_e32 v155, v133
	v_lshl_add_u32 v156, v10, 1, v0
	v_mov_b32_e32 v157, v133
	v_mov_b64_e32 v[158:159], 0x580
	v_mov_b64_e32 v[160:161], 0x57f
	v_add_u32_e32 v165, s43, v164
	v_add_u32_e32 v166, s44, v164
	v_add_u32_e32 v167, 0, v6
	s_barrier
	s_mov_b32 s53, 0
	s_mov_b32 s54, 0
	s_branch .LBB0_1560

.LBB0_1559:
	s_andn2_b64 vcc, exec, s[0:1]
	s_mov_b32 s54, s53
	s_mov_b32 s18, s10
	s_mov_b32 s16, s8
	s_mov_b64 s[20:21], s[14:15]
	s_mov_b64 s[22:23], s[12:13]
	s_cbranch_vccz .LBB0_1569
.LBB0_1560:
	s_add_i32 s38, s38, 1
	s_mul_i32 s0, s38, s42
	s_mul_hi_u32 s1, s38, s26
	s_add_i32 s1, s1, s0
	s_mul_i32 s0, s38, s26
	s_add_u32 s12, s0, s27
	s_addc_u32 s13, s1, s34
	s_mov_b32 s53, 0
	s_cmp_lg_u32 s26, 0x100
	s_cbranch_scc1 .Lts0_md
	s_cmpk_lt_u32 s12, 0x500
	s_cbranch_scc1 .Lts0_md
	s_mov_b32 s53, 1
	s_cmpk_lt_u32 s12, 0x580
	s_cbranch_scc1 .Lts0_md
	s_mov_b32 s53, 0
	s_cmpk_lt_u32 s12, 0x600
	s_cbranch_scc0 .Lts0_md
	s_mov_b32 s53, 2
	s_sub_u32 s12, s12, 0x80
.Lts0_md:
	v_cmp_gt_i64_e32 vcc, s[12:13], v[160:161]
	v_cmp_lt_i64_e64 s[0:1], s[12:13], v[158:159]
	s_cbranch_vccnz .LBB0_1562
	s_ashr_i32 s8, s12, 31
	s_lshr_b32 s8, s8, 29
	s_add_i32 s8, s12, s8
	s_ashr_i32 s9, s8, 3
	s_and_b32 s8, s8, -8
	s_sub_i32 s8, s12, s8
	s_cmp_lt_i32 s8, 0
	s_cselect_b32 s10, s35, 0xb0
	s_mul_i32 s8, s10, s8
	s_add_i32 s8, s8, s9
	s_mul_hi_i32 s9, s8, 0x2e8ba2e9
	s_lshr_b32 s10, s9, 31
	s_ashr_i32 s9, s9, 4
	s_add_i32 s9, s9, s10
	s_lshl_b32 s10, s9, 2
	s_sub_i32 s11, 64, s10
	s_min_i32 s11, s11, 4
	s_abs_i32 s12, s11
	v_cvt_f32_u32_e32 v0, s12
	s_sub_i32 s14, 0, s12
	s_mulk_i32 s9, 0x58
	s_sub_i32 s8, s8, s9
	v_rcp_iflag_f32_e32 v0, v0
	s_abs_i32 s9, s8
	s_xor_b32 s13, s8, s11
	s_ashr_i32 s13, s13, 31
	v_mul_f32_e32 v0, 0x4f7ffffe, v0
	v_cvt_u32_f32_e32 v0, v0
	s_nop 0
	v_readfirstlane_b32 s15, v0
	s_mul_i32 s14, s14, s15
	s_mul_hi_u32 s14, s15, s14
	s_add_i32 s15, s15, s14
	s_mul_hi_u32 s14, s9, s15
	s_mul_i32 s15, s14, s12
	s_sub_i32 s9, s9, s15
	s_add_i32 s24, s14, 1
	s_sub_i32 s15, s9, s12
	s_cmp_ge_u32 s9, s12
	s_cselect_b32 s14, s24, s14
	s_cselect_b32 s9, s15, s9
	s_add_i32 s15, s14, 1
	s_cmp_ge_u32 s9, s12
	s_cselect_b32 s9, s15, s14
	s_xor_b32 s9, s9, s13
	s_sub_i32 s9, s9, s13
	s_mul_i32 s11, s9, s11
	s_sub_i32 s8, s8, s11
	s_add_i32 s8, s8, s10
	s_ashr_i32 s10, s8, 3
	s_mul_i32 s10, s10, 3
	s_add_i32 s10, s10, s9
	s_mul_hi_i32 s9, s10, 0x2e8ba2e9
	s_lshr_b32 s11, s9, 31
	s_ashr_i32 s9, s9, 2
	s_add_i32 s9, s9, s11
	s_mul_i32 s9, s9, 22
	s_sub_i32 s10, s10, s9
.LBB0_1562:
	s_ashr_i32 s9, s8, 31
	s_lshl_b64 s[12:13], s[8:9], 19
	s_add_u32 s12, s28, s12
	s_addc_u32 s13, s29, s13
	s_cmp_eq_u32 s53, 2
	s_cselect_b32 s55, 0x40000, 0
	s_add_u32 s12, s12, s55
	s_addc_u32 s13, s13, 0
	s_and_b64 s[14:15], s[0:1], exec
	s_cselect_b32 s9, s13, s23
	s_cselect_b32 s45, s12, s22
	s_ashr_i32 s11, s10, 31
	s_lshl_b64 s[14:15], s[10:11], 19
	s_add_u32 s14, s30, s14
	s_addc_u32 s15, s31, s15
	s_and_b64 s[24:25], s[0:1], exec
	s_cselect_b32 s11, s15, s21
	s_cselect_b32 s46, s14, s20
	s_add_u32 s47, s20, 0x10000
	s_addc_u32 s48, s21, 0
	s_add_u32 s20, s22, 0x40080
	v_mov_b32_e32 v0, 0
	s_addc_u32 s21, s23, 0
	s_mov_b32 s49, -2
	v_mov_b32_e32 v1, v0
	v_mov_b32_e32 v2, v0
	v_mov_b32_e32 v3, v0
	v_mov_b32_e32 v8, v0
	v_mov_b32_e32 v9, v0
	v_mov_b32_e32 v10, v0
	v_mov_b32_e32 v11, v0
	v_mov_b32_e32 v16, v0
	v_mov_b32_e32 v17, v0
	v_mov_b32_e32 v18, v0
	v_mov_b32_e32 v19, v0
	v_mov_b32_e32 v24, v0
	v_mov_b32_e32 v25, v0
	v_mov_b32_e32 v26, v0
	v_mov_b32_e32 v27, v0
	v_mov_b32_e32 v32, v0
	v_mov_b32_e32 v33, v0
	v_mov_b32_e32 v34, v0
	v_mov_b32_e32 v35, v0
	v_mov_b32_e32 v40, v0
	v_mov_b32_e32 v41, v0
	v_mov_b32_e32 v42, v0
	v_mov_b32_e32 v43, v0
	v_mov_b32_e32 v48, v0
	v_mov_b32_e32 v49, v0
	v_mov_b32_e32 v50, v0
	v_mov_b32_e32 v51, v0
	v_mov_b32_e32 v56, v0
	v_mov_b32_e32 v57, v0
	v_mov_b32_e32 v58, v0
	v_mov_b32_e32 v59, v0
	v_mov_b32_e32 v4, v0
	v_mov_b32_e32 v5, v0
	v_mov_b32_e32 v6, v0
	v_mov_b32_e32 v7, v0
	v_mov_b32_e32 v12, v0
	v_mov_b32_e32 v13, v0
	v_mov_b32_e32 v14, v0
	v_mov_b32_e32 v15, v0
	v_mov_b32_e32 v20, v0
	v_mov_b32_e32 v21, v0
	v_mov_b32_e32 v22, v0
	v_mov_b32_e32 v23, v0
	v_mov_b32_e32 v28, v0
	v_mov_b32_e32 v29, v0
	v_mov_b32_e32 v30, v0
	v_mov_b32_e32 v31, v0
	v_mov_b32_e32 v36, v0
	v_mov_b32_e32 v37, v0
	v_mov_b32_e32 v38, v0
	v_mov_b32_e32 v39, v0
	v_mov_b32_e32 v44, v0
	v_mov_b32_e32 v45, v0
	v_mov_b32_e32 v46, v0
	v_mov_b32_e32 v47, v0
	v_mov_b32_e32 v52, v0
	v_mov_b32_e32 v53, v0
	v_mov_b32_e32 v54, v0
	v_mov_b32_e32 v55, v0
	v_mov_b32_e32 v60, v0
	v_mov_b32_e32 v61, v0
	v_mov_b32_e32 v62, v0
	v_mov_b32_e32 v63, v0
	v_mov_b32_e32 v64, v0
	v_mov_b32_e32 v65, v0
	v_mov_b32_e32 v66, v0
	v_mov_b32_e32 v67, v0
	v_mov_b32_e32 v72, v0
	v_mov_b32_e32 v73, v0
	v_mov_b32_e32 v74, v0
	v_mov_b32_e32 v75, v0
	v_mov_b32_e32 v80, v0
	v_mov_b32_e32 v81, v0
	v_mov_b32_e32 v82, v0
	v_mov_b32_e32 v83, v0
	v_mov_b32_e32 v88, v0
	v_mov_b32_e32 v89, v0
	v_mov_b32_e32 v90, v0
	v_mov_b32_e32 v91, v0
	v_mov_b32_e32 v96, v0
	v_mov_b32_e32 v97, v0
	v_mov_b32_e32 v98, v0
	v_mov_b32_e32 v99, v0
	v_mov_b32_e32 v104, v0
	v_mov_b32_e32 v105, v0
	v_mov_b32_e32 v106, v0
	v_mov_b32_e32 v107, v0
	v_mov_b32_e32 v112, v0
	v_mov_b32_e32 v113, v0
	v_mov_b32_e32 v114, v0
	v_mov_b32_e32 v115, v0
	v_mov_b32_e32 v120, v0
	v_mov_b32_e32 v121, v0
	v_mov_b32_e32 v122, v0
	v_mov_b32_e32 v123, v0
	v_mov_b32_e32 v68, v0
	v_mov_b32_e32 v69, v0
	v_mov_b32_e32 v70, v0
	v_mov_b32_e32 v71, v0
	v_mov_b32_e32 v76, v0
	v_mov_b32_e32 v77, v0
	v_mov_b32_e32 v78, v0
	v_mov_b32_e32 v79, v0
	v_mov_b32_e32 v84, v0
	v_mov_b32_e32 v85, v0
	v_mov_b32_e32 v86, v0
	v_mov_b32_e32 v87, v0
	v_mov_b32_e32 v92, v0
	v_mov_b32_e32 v93, v0
	v_mov_b32_e32 v94, v0
	v_mov_b32_e32 v95, v0
	v_mov_b32_e32 v100, v0
	v_mov_b32_e32 v101, v0
	v_mov_b32_e32 v102, v0
	v_mov_b32_e32 v103, v0
	v_mov_b32_e32 v108, v0
	v_mov_b32_e32 v109, v0
	v_mov_b32_e32 v110, v0
	v_mov_b32_e32 v111, v0
	v_mov_b32_e32 v116, v0
	v_mov_b32_e32 v117, v0
	v_mov_b32_e32 v118, v0
	v_mov_b32_e32 v119, v0
	v_mov_b32_e32 v124, v0
	v_mov_b32_e32 v125, v0
	v_mov_b32_e32 v126, v0
	v_mov_b32_e32 v127, v0
.LBB0_1563:
	ds_read_b128 v[168:171], v165
	ds_read_b128 v[172:175], v165 offset:1024
	ds_read_b128 v[176:179], v165 offset:2048
	ds_read_b128 v[180:183], v165 offset:3072
	ds_read_b128 v[184:187], v166
	ds_read_b128 v[188:191], v166 offset:1024
	ds_read_b128 v[192:195], v166 offset:2048
	ds_read_b128 v[196:199], v166 offset:3072
	s_add_u32 s22, s20, 0xfffc0080
	s_addc_u32 s23, s21, -1
	s_cmp_eq_u32 s49, 12
	s_cselect_b32 s25, s9, s23
	s_cselect_b32 s24, s45, s22
	s_cselect_b32 s23, s11, s48
	s_cselect_b32 s22, s46, s47
	v_lshl_add_u64 v[162:163], s[20:21], 0, v[156:157]
	s_add_i32 m0, s17, 0xc000
	ds_read_b128 v[210:213], v167
	ds_read_b128 v[214:217], v167 offset:1024
	ds_read_b128 v[218:221], v167 offset:2048
	ds_read_b128 v[222:225], v167 offset:3072
	ds_read_b128 v[226:229], v167 offset:4096
	ds_read_b128 v[230:233], v167 offset:5120
	ds_read_b128 v[234:237], v167 offset:6144
	ds_read_b128 v[238:241], v167 offset:7168
	global_load_lds_dwordx4 v[162:163], off
	v_lshl_add_u64 v[162:163], s[20:21], 0, v[154:155]
	s_add_i32 m0, s17, 0xe000
	s_nop 0
	global_load_lds_dwordx4 v[162:163], off
	s_waitcnt vmcnt(8)
	s_waitcnt lgkmcnt(0)
	s_barrier
	s_setprio 1
	s_waitcnt lgkmcnt(0)
	v_mfma_f32_16x16x32_bf16 v[124:127], v[168:171], v[210:213], v[124:127]
	v_mfma_f32_16x16x32_bf16 v[116:119], v[176:179], v[210:213], v[116:119]
	v_mfma_f32_16x16x32_bf16 v[108:111], v[168:171], v[218:221], v[108:111]
	v_mfma_f32_16x16x32_bf16 v[100:103], v[176:179], v[218:221], v[100:103]
	v_mfma_f32_16x16x32_bf16 v[92:95], v[168:171], v[226:229], v[92:95]
	v_mfma_f32_16x16x32_bf16 v[84:87], v[176:179], v[226:229], v[84:87]
	v_mfma_f32_16x16x32_bf16 v[76:79], v[168:171], v[234:237], v[76:79]
	v_mfma_f32_16x16x32_bf16 v[68:71], v[176:179], v[234:237], v[68:71]
	v_mfma_f32_16x16x32_bf16 v[124:127], v[172:175], v[214:217], v[124:127]
	v_mfma_f32_16x16x32_bf16 v[116:119], v[180:183], v[214:217], v[116:119]
	v_mfma_f32_16x16x32_bf16 v[108:111], v[172:175], v[222:225], v[108:111]
	v_mfma_f32_16x16x32_bf16 v[100:103], v[180:183], v[222:225], v[100:103]
	v_mfma_f32_16x16x32_bf16 v[92:95], v[172:175], v[230:233], v[92:95]
	v_mfma_f32_16x16x32_bf16 v[84:87], v[180:183], v[230:233], v[84:87]
	v_mfma_f32_16x16x32_bf16 v[76:79], v[172:175], v[238:241], v[76:79]
	v_mfma_f32_16x16x32_bf16 v[68:71], v[180:183], v[238:241], v[68:71]
	s_setprio 0
	s_setprio 1
	v_mfma_f32_16x16x32_bf16 v[120:123], v[184:187], v[210:213], v[120:123]
	v_mfma_f32_16x16x32_bf16 v[112:115], v[192:195], v[210:213], v[112:115]
	v_mfma_f32_16x16x32_bf16 v[104:107], v[184:187], v[218:221], v[104:107]
	v_mfma_f32_16x16x32_bf16 v[96:99], v[192:195], v[218:221], v[96:99]
	v_mfma_f32_16x16x32_bf16 v[88:91], v[184:187], v[226:229], v[88:91]
	v_mfma_f32_16x16x32_bf16 v[80:83], v[192:195], v[226:229], v[80:83]
	v_mfma_f32_16x16x32_bf16 v[72:75], v[184:187], v[234:237], v[72:75]
	v_mfma_f32_16x16x32_bf16 v[64:67], v[192:195], v[234:237], v[64:67]
	v_mfma_f32_16x16x32_bf16 v[120:123], v[188:191], v[214:217], v[120:123]
	v_mfma_f32_16x16x32_bf16 v[112:115], v[196:199], v[214:217], v[112:115]
	v_mfma_f32_16x16x32_bf16 v[104:107], v[188:191], v[222:225], v[104:107]
	v_mfma_f32_16x16x32_bf16 v[96:99], v[196:199], v[222:225], v[96:99]
	v_mfma_f32_16x16x32_bf16 v[88:91], v[188:191], v[230:233], v[88:91]
	v_mfma_f32_16x16x32_bf16 v[80:83], v[196:199], v[230:233], v[80:83]
	v_mfma_f32_16x16x32_bf16 v[72:75], v[188:191], v[238:241], v[72:75]
	v_mfma_f32_16x16x32_bf16 v[64:67], v[196:199], v[238:241], v[64:67]
	s_setprio 0
	s_barrier
	s_add_i32 s50, s43, s33
	v_lshl_add_u64 v[162:163], s[22:23], 0, v[132:133]
	s_mov_b32 m0, s50
	s_cmp_lg_u32 s54, 0
	s_cbranch_scc1 .Lts0_skip1
	ds_read_b128 v[210:213], v167 offset:16384
	ds_read_b128 v[214:217], v167 offset:17408
	ds_read_b128 v[218:221], v167 offset:18432
	ds_read_b128 v[222:225], v167 offset:19456
	ds_read_b128 v[226:229], v167 offset:20480
	ds_read_b128 v[230:233], v167 offset:21504
	ds_read_b128 v[234:237], v167 offset:22528
	ds_read_b128 v[238:241], v167 offset:23552
.Lts0_skip1:
	global_load_lds_dwordx4 v[162:163], off
	s_add_i32 m0, s50, 0x2000
	s_add_u32 s50, s22, 0x4000
	v_lshl_add_u64 v[162:163], s[22:23], 0, v[128:129]
	s_addc_u32 s51, s23, 0
	s_add_i32 s52, s44, s33
	global_load_lds_dwordx4 v[162:163], off
	v_lshl_add_u64 v[162:163], s[50:51], 0, v[132:133]
	s_mov_b32 m0, s52
	v_lshl_add_u64 v[200:201], s[24:25], 0, v[130:131]
	global_load_lds_dwordx4 v[162:163], off
	v_lshl_add_u64 v[162:163], s[50:51], 0, v[128:129]
	s_add_i32 m0, s52, 0x2000
	s_nop 0
	global_load_lds_dwordx4 v[162:163], off
	v_lshl_add_u64 v[162:163], s[24:25], 0, v[134:135]
	s_mov_b32 m0, s17
	s_nop 0
	global_load_lds_dwordx4 v[162:163], off
	s_mov_b32 m0, s19
	s_nop 0
	global_load_lds_dwordx4 v[200:201], off
	s_waitcnt vmcnt(8)
	s_waitcnt lgkmcnt(0)
	s_barrier
	s_cmp_lg_u32 s54, 0
	s_cbranch_scc1 .Lts0_skip0
	s_setprio 1
	s_waitcnt lgkmcnt(0)
	v_mfma_f32_16x16x32_bf16 v[60:63], v[168:171], v[210:213], v[60:63]
	v_mfma_f32_16x16x32_bf16 v[52:55], v[176:179], v[210:213], v[52:55]
	v_mfma_f32_16x16x32_bf16 v[44:47], v[168:171], v[218:221], v[44:47]
	v_mfma_f32_16x16x32_bf16 v[36:39], v[176:179], v[218:221], v[36:39]
	v_mfma_f32_16x16x32_bf16 v[28:31], v[168:171], v[226:229], v[28:31]
	v_mfma_f32_16x16x32_bf16 v[20:23], v[176:179], v[226:229], v[20:23]
	v_mfma_f32_16x16x32_bf16 v[12:15], v[168:171], v[234:237], v[12:15]
	v_mfma_f32_16x16x32_bf16 v[4:7], v[176:179], v[234:237], v[4:7]
	v_mfma_f32_16x16x32_bf16 v[60:63], v[172:175], v[214:217], v[60:63]
	v_mfma_f32_16x16x32_bf16 v[52:55], v[180:183], v[214:217], v[52:55]
	v_mfma_f32_16x16x32_bf16 v[44:47], v[172:175], v[222:225], v[44:47]
	v_mfma_f32_16x16x32_bf16 v[36:39], v[180:183], v[222:225], v[36:39]
	v_mfma_f32_16x16x32_bf16 v[28:31], v[172:175], v[230:233], v[28:31]
	v_mfma_f32_16x16x32_bf16 v[20:23], v[180:183], v[230:233], v[20:23]
	v_mfma_f32_16x16x32_bf16 v[12:15], v[172:175], v[238:241], v[12:15]
	v_mfma_f32_16x16x32_bf16 v[4:7], v[180:183], v[238:241], v[4:7]
	s_setprio 0
	s_setprio 1
	v_mfma_f32_16x16x32_bf16 v[56:59], v[184:187], v[210:213], v[56:59]
	v_mfma_f32_16x16x32_bf16 v[48:51], v[192:195], v[210:213], v[48:51]
	v_mfma_f32_16x16x32_bf16 v[40:43], v[184:187], v[218:221], v[40:43]
	v_mfma_f32_16x16x32_bf16 v[32:35], v[192:195], v[218:221], v[32:35]
	v_mfma_f32_16x16x32_bf16 v[24:27], v[184:187], v[226:229], v[24:27]
	v_mfma_f32_16x16x32_bf16 v[16:19], v[192:195], v[226:229], v[16:19]
	v_mfma_f32_16x16x32_bf16 v[8:11], v[184:187], v[234:237], v[8:11]
	v_mfma_f32_16x16x32_bf16 v[0:3], v[192:195], v[234:237], v[0:3]
	v_mfma_f32_16x16x32_bf16 v[56:59], v[188:191], v[214:217], v[56:59]
	v_mfma_f32_16x16x32_bf16 v[48:51], v[196:199], v[214:217], v[48:51]
	v_mfma_f32_16x16x32_bf16 v[40:43], v[188:191], v[222:225], v[40:43]
	v_mfma_f32_16x16x32_bf16 v[32:35], v[196:199], v[222:225], v[32:35]
	v_mfma_f32_16x16x32_bf16 v[24:27], v[188:191], v[230:233], v[24:27]
	v_mfma_f32_16x16x32_bf16 v[16:19], v[196:199], v[230:233], v[16:19]
	v_mfma_f32_16x16x32_bf16 v[8:11], v[188:191], v[238:241], v[8:11]
	v_mfma_f32_16x16x32_bf16 v[0:3], v[196:199], v[238:241], v[0:3]
	s_setprio 0
.Lts0_skip0:
	s_barrier
	s_add_i32 s50, 0, 0x18000
	s_add_i32 s51, 0, 0x1c000
	v_add_u32_e32 v180, s50, v164
	v_add_u32_e32 v196, s51, v164
	ds_read_b128 v[168:171], v180
	ds_read_b128 v[172:175], v180 offset:1024
	ds_read_b128 v[176:179], v180 offset:2048
	ds_read_b128 v[180:183], v180 offset:3072
	ds_read_b128 v[184:187], v196
	ds_read_b128 v[188:191], v196 offset:1024
	ds_read_b128 v[192:195], v196 offset:2048
	ds_read_b128 v[196:199], v196 offset:3072
	s_add_u32 s24, s24, 0x40000
	s_addc_u32 s25, s25, 0
	s_mov_b32 m0, s36
	v_lshl_add_u64 v[204:205], s[24:25], 0, v[134:135]
	ds_read_b128 v[210:213], v167 offset:32768
	ds_read_b128 v[214:217], v167 offset:33792
	ds_read_b128 v[218:221], v167 offset:34816
	ds_read_b128 v[222:225], v167 offset:35840
	ds_read_b128 v[226:229], v167 offset:36864
	ds_read_b128 v[230:233], v167 offset:37888
	ds_read_b128 v[234:237], v167 offset:38912
	ds_read_b128 v[238:241], v167 offset:39936
	global_load_lds_dwordx4 v[204:205], off
	v_lshl_add_u64 v[204:205], s[24:25], 0, v[130:131]
	s_mov_b32 m0, s37
	s_nop 0
	global_load_lds_dwordx4 v[204:205], off
	s_waitcnt vmcnt(8)
	s_waitcnt lgkmcnt(0)
	s_barrier
	s_setprio 1
	s_waitcnt lgkmcnt(0)
	v_mfma_f32_16x16x32_bf16 v[124:127], v[168:171], v[210:213], v[124:127]
	v_mfma_f32_16x16x32_bf16 v[116:119], v[176:179], v[210:213], v[116:119]
	v_mfma_f32_16x16x32_bf16 v[108:111], v[168:171], v[218:221], v[108:111]
	v_mfma_f32_16x16x32_bf16 v[100:103], v[176:179], v[218:221], v[100:103]
	v_mfma_f32_16x16x32_bf16 v[92:95], v[168:171], v[226:229], v[92:95]
	v_mfma_f32_16x16x32_bf16 v[84:87], v[176:179], v[226:229], v[84:87]
	v_mfma_f32_16x16x32_bf16 v[76:79], v[168:171], v[234:237], v[76:79]
	v_mfma_f32_16x16x32_bf16 v[68:71], v[176:179], v[234:237], v[68:71]
	v_mfma_f32_16x16x32_bf16 v[124:127], v[172:175], v[214:217], v[124:127]
	v_mfma_f32_16x16x32_bf16 v[116:119], v[180:183], v[214:217], v[116:119]
	v_mfma_f32_16x16x32_bf16 v[108:111], v[172:175], v[222:225], v[108:111]
	v_mfma_f32_16x16x32_bf16 v[100:103], v[180:183], v[222:225], v[100:103]
	v_mfma_f32_16x16x32_bf16 v[92:95], v[172:175], v[230:233], v[92:95]
	v_mfma_f32_16x16x32_bf16 v[84:87], v[180:183], v[230:233], v[84:87]
	v_mfma_f32_16x16x32_bf16 v[76:79], v[172:175], v[238:241], v[76:79]
	v_mfma_f32_16x16x32_bf16 v[68:71], v[180:183], v[238:241], v[68:71]
	s_setprio 0
	s_setprio 1
	v_mfma_f32_16x16x32_bf16 v[120:123], v[184:187], v[210:213], v[120:123]
	v_mfma_f32_16x16x32_bf16 v[112:115], v[192:195], v[210:213], v[112:115]
	v_mfma_f32_16x16x32_bf16 v[104:107], v[184:187], v[218:221], v[104:107]
	v_mfma_f32_16x16x32_bf16 v[96:99], v[192:195], v[218:221], v[96:99]
	v_mfma_f32_16x16x32_bf16 v[88:91], v[184:187], v[226:229], v[88:91]
	v_mfma_f32_16x16x32_bf16 v[80:83], v[192:195], v[226:229], v[80:83]
	v_mfma_f32_16x16x32_bf16 v[72:75], v[184:187], v[234:237], v[72:75]
	v_mfma_f32_16x16x32_bf16 v[64:67], v[192:195], v[234:237], v[64:67]
	v_mfma_f32_16x16x32_bf16 v[120:123], v[188:191], v[214:217], v[120:123]
	v_mfma_f32_16x16x32_bf16 v[112:115], v[196:199], v[214:217], v[112:115]
	v_mfma_f32_16x16x32_bf16 v[104:107], v[188:191], v[222:225], v[104:107]
	v_mfma_f32_16x16x32_bf16 v[96:99], v[196:199], v[222:225], v[96:99]
	v_mfma_f32_16x16x32_bf16 v[88:91], v[188:191], v[230:233], v[88:91]
	v_mfma_f32_16x16x32_bf16 v[80:83], v[196:199], v[230:233], v[80:83]
	v_mfma_f32_16x16x32_bf16 v[72:75], v[188:191], v[238:241], v[72:75]
	v_mfma_f32_16x16x32_bf16 v[64:67], v[196:199], v[238:241], v[64:67]
	s_setprio 0
	s_barrier
	s_add_u32 s24, s22, 0x8000
	s_addc_u32 s25, s23, 0
	s_add_i32 s50, s50, s33
	v_lshl_add_u64 v[204:205], s[24:25], 0, v[132:133]
	s_mov_b32 m0, s50
	s_cmp_lg_u32 s54, 0
	s_cbranch_scc1 .Lts0_skip3
	ds_read_b128 v[210:213], v167 offset:49152
	ds_read_b128 v[214:217], v167 offset:50176
	ds_read_b128 v[218:221], v167 offset:51200
	ds_read_b128 v[222:225], v167 offset:52224
	ds_read_b128 v[226:229], v167 offset:53248
	ds_read_b128 v[230:233], v167 offset:54272
	ds_read_b128 v[234:237], v167 offset:55296
	ds_read_b128 v[238:241], v167 offset:56320
.Lts0_skip3:
	global_load_lds_dwordx4 v[204:205], off
	s_add_i32 m0, s50, 0x2000
	s_add_u32 s22, s22, 0xc000
	v_lshl_add_u64 v[204:205], s[24:25], 0, v[128:129]
	s_addc_u32 s23, s23, 0
	s_add_i32 s24, s51, s33
	global_load_lds_dwordx4 v[204:205], off
	v_lshl_add_u64 v[204:205], s[22:23], 0, v[132:133]
	s_mov_b32 m0, s24
	v_lshl_add_u64 v[162:163], v[162:163], 0, s[4:5]
	global_load_lds_dwordx4 v[204:205], off
	v_lshl_add_u64 v[204:205], s[22:23], 0, v[128:129]
	s_add_i32 m0, s24, 0x2000
	s_nop 0
	global_load_lds_dwordx4 v[204:205], off
	s_mov_b32 m0, s40
	s_nop 0
	global_load_lds_dwordx4 v[162:163], off
	v_lshl_add_u64 v[162:163], v[200:201], 0, s[4:5]
	s_mov_b32 m0, s41
	s_nop 0
	global_load_lds_dwordx4 v[162:163], off
	s_waitcnt vmcnt(8)
	s_waitcnt lgkmcnt(0)
	s_barrier
	s_cmp_lg_u32 s54, 0
	s_cbranch_scc1 .Lts0_skip2
	s_setprio 1
	s_waitcnt lgkmcnt(0)
	v_mfma_f32_16x16x32_bf16 v[60:63], v[168:171], v[210:213], v[60:63]
	v_mfma_f32_16x16x32_bf16 v[52:55], v[176:179], v[210:213], v[52:55]
	v_mfma_f32_16x16x32_bf16 v[44:47], v[168:171], v[218:221], v[44:47]
	v_mfma_f32_16x16x32_bf16 v[36:39], v[176:179], v[218:221], v[36:39]
	v_mfma_f32_16x16x32_bf16 v[28:31], v[168:171], v[226:229], v[28:31]
	v_mfma_f32_16x16x32_bf16 v[20:23], v[176:179], v[226:229], v[20:23]
	v_mfma_f32_16x16x32_bf16 v[12:15], v[168:171], v[234:237], v[12:15]
	v_mfma_f32_16x16x32_bf16 v[4:7], v[176:179], v[234:237], v[4:7]
	v_mfma_f32_16x16x32_bf16 v[60:63], v[172:175], v[214:217], v[60:63]
	v_mfma_f32_16x16x32_bf16 v[52:55], v[180:183], v[214:217], v[52:55]
	v_mfma_f32_16x16x32_bf16 v[44:47], v[172:175], v[222:225], v[44:47]
	v_mfma_f32_16x16x32_bf16 v[36:39], v[180:183], v[222:225], v[36:39]
	v_mfma_f32_16x16x32_bf16 v[28:31], v[172:175], v[230:233], v[28:31]
	v_mfma_f32_16x16x32_bf16 v[20:23], v[180:183], v[230:233], v[20:23]
	v_mfma_f32_16x16x32_bf16 v[12:15], v[172:175], v[238:241], v[12:15]
	v_mfma_f32_16x16x32_bf16 v[4:7], v[180:183], v[238:241], v[4:7]
	s_setprio 0
	s_setprio 1
	v_mfma_f32_16x16x32_bf16 v[56:59], v[184:187], v[210:213], v[56:59]
	v_mfma_f32_16x16x32_bf16 v[48:51], v[192:195], v[210:213], v[48:51]
	v_mfma_f32_16x16x32_bf16 v[40:43], v[184:187], v[218:221], v[40:43]
	v_mfma_f32_16x16x32_bf16 v[32:35], v[192:195], v[218:221], v[32:35]
	v_mfma_f32_16x16x32_bf16 v[24:27], v[184:187], v[226:229], v[24:27]
	v_mfma_f32_16x16x32_bf16 v[16:19], v[192:195], v[226:229], v[16:19]
	v_mfma_f32_16x16x32_bf16 v[8:11], v[184:187], v[234:237], v[8:11]
	v_mfma_f32_16x16x32_bf16 v[0:3], v[192:195], v[234:237], v[0:3]
	v_mfma_f32_16x16x32_bf16 v[56:59], v[188:191], v[214:217], v[56:59]
	v_mfma_f32_16x16x32_bf16 v[48:51], v[196:199], v[214:217], v[48:51]
	v_mfma_f32_16x16x32_bf16 v[40:43], v[188:191], v[222:225], v[40:43]
	v_mfma_f32_16x16x32_bf16 v[32:35], v[196:199], v[222:225], v[32:35]
	v_mfma_f32_16x16x32_bf16 v[24:27], v[188:191], v[230:233], v[24:27]
	v_mfma_f32_16x16x32_bf16 v[16:19], v[196:199], v[230:233], v[16:19]
	v_mfma_f32_16x16x32_bf16 v[8:11], v[188:191], v[238:241], v[8:11]
	v_mfma_f32_16x16x32_bf16 v[0:3], v[196:199], v[238:241], v[0:3]
	s_setprio 0
.Lts0_skip2:
	s_barrier
	s_add_i32 s49, s49, 2
	s_add_u32 s47, s47, 0x10000
	s_addc_u32 s48, s48, 0
	s_add_u32 s20, s20, 0x100
	s_addc_u32 s21, s21, 0
	s_cmp_gt_u32 s49, 13
	s_cbranch_scc0 .LBB0_1563
	s_and_b64 vcc, exec, s[6:7]
	s_cbranch_vccz .LBB0_1566
	s_barrier
.LBB0_1566:
	v_mul_f32_e32 v162, 0xbfb8aa3b, v124
	v_exp_f32_e32 v168, v162
	v_mul_f32_e32 v162, 0xbfb8aa3b, v125
	v_exp_f32_e32 v169, v162
	v_mul_f32_e32 v170, 0xbfb8aa3b, v126
	v_mul_f32_e32 v171, 0xbfb8aa3b, v127
	v_exp_f32_e32 v170, v170
	v_exp_f32_e32 v171, v171
	v_add_f32_e32 v168, 1.0, v168
	v_add_f32_e32 v169, 1.0, v169
	v_rcp_f32_e32 v168, v168
	v_rcp_f32_e32 v169, v169
	v_add_f32_e32 v170, 1.0, v170
	v_add_f32_e32 v171, 1.0, v171
	v_rcp_f32_e32 v170, v170
	v_rcp_f32_e32 v171, v171
	v_pk_mul_f32 v[124:125], v[124:125], v[168:169]
	s_lshl_b32 s9, s18, 7
	v_pk_mul_f32 v[120:121], v[124:125], v[120:121]
	v_pk_mul_f32 v[124:125], v[126:127], v[170:171]
	v_cvt_pk_bf16_f32 v120, v120, v121
	v_mul_f32_e32 v121, 0xbfb8aa3b, v116
	v_pk_mul_f32 v[122:123], v[124:125], v[122:123]
	v_exp_f32_e32 v124, v121
	v_mul_f32_e32 v121, 0xbfb8aa3b, v117
	v_exp_f32_e32 v125, v121
	v_cvt_pk_bf16_f32 v121, v122, v123
	v_add_f32_e32 v122, 1.0, v124
	v_mul_f32_e32 v124, 0xbfb8aa3b, v118
	v_add_f32_e32 v123, 1.0, v125
	v_mul_f32_e32 v125, 0xbfb8aa3b, v119
	v_exp_f32_e32 v124, v124
	v_exp_f32_e32 v125, v125
	v_rcp_f32_e32 v122, v122
	v_rcp_f32_e32 v123, v123
	v_add_f32_e32 v124, 1.0, v124
	v_add_f32_e32 v125, 1.0, v125
	v_rcp_f32_e32 v124, v124
	v_rcp_f32_e32 v125, v125
	v_pk_mul_f32 v[116:117], v[116:117], v[122:123]
	s_or_b32 s9, s9, s39
	v_pk_mul_f32 v[112:113], v[116:117], v[112:113]
	s_mul_i32 s11, s16, 44
	s_ashr_i32 s9, s9, 6
	v_cvt_pk_bf16_f32 v122, v112, v113
	v_pk_mul_f32 v[112:113], v[118:119], v[124:125]
	s_add_i32 s20, s9, s11
	v_pk_mul_f32 v[112:113], v[112:113], v[114:115]
	v_mul_f32_e32 v114, 0xbfb8aa3b, v108
	v_mul_f32_e32 v115, 0xbfb8aa3b, v109
	s_ashr_i32 s21, s20, 31
	v_exp_f32_e32 v114, v114
	v_exp_f32_e32 v115, v115
	s_lshl_b64 s[20:21], s[20:21], 15
	s_cmp_eq_u32 s54, 2
	s_cselect_b32 s55, 0x4000, 0
	s_add_u32 s20, s20, s55
	s_addc_u32 s21, s21, 0
	v_lshl_add_u64 v[162:163], v[136:137], 0, s[20:21]
	v_cvt_pk_bf16_f32 v123, v112, v113
	v_lshl_add_u64 v[112:113], v[162:163], 0, v[138:139]
	global_store_dwordx4 v[112:113], v[120:123], off
	v_add_f32_e32 v112, 1.0, v114
	v_add_f32_e32 v113, 1.0, v115
	v_mul_f32_e32 v114, 0xbfb8aa3b, v110
	v_mul_f32_e32 v115, 0xbfb8aa3b, v111
	v_exp_f32_e32 v114, v114
	v_exp_f32_e32 v115, v115
	v_rcp_f32_e32 v112, v112
	v_rcp_f32_e32 v113, v113
	v_add_f32_e32 v114, 1.0, v114
	v_add_f32_e32 v115, 1.0, v115
	v_rcp_f32_e32 v114, v114
	v_rcp_f32_e32 v115, v115
	v_pk_mul_f32 v[108:109], v[108:109], v[112:113]
	s_andn2_b64 vcc, exec, s[0:1]
	v_pk_mul_f32 v[104:105], v[108:109], v[104:105]
	v_pk_mul_f32 v[108:109], v[110:111], v[114:115]
	v_cvt_pk_bf16_f32 v104, v104, v105
	v_mul_f32_e32 v105, 0xbfb8aa3b, v100
	v_pk_mul_f32 v[106:107], v[108:109], v[106:107]
	v_exp_f32_e32 v108, v105
	v_mul_f32_e32 v105, 0xbfb8aa3b, v101
	v_exp_f32_e32 v109, v105
	v_cvt_pk_bf16_f32 v105, v106, v107
	v_add_f32_e32 v106, 1.0, v108
	v_mul_f32_e32 v108, 0xbfb8aa3b, v102
	v_add_f32_e32 v107, 1.0, v109
	v_mul_f32_e32 v109, 0xbfb8aa3b, v103
	v_exp_f32_e32 v108, v108
	v_exp_f32_e32 v109, v109
	v_rcp_f32_e32 v106, v106
	v_rcp_f32_e32 v107, v107
	v_add_f32_e32 v108, 1.0, v108
	v_add_f32_e32 v109, 1.0, v109
	v_rcp_f32_e32 v108, v108
	v_rcp_f32_e32 v109, v109
	v_pk_mul_f32 v[100:101], v[100:101], v[106:107]
	s_mov_b64 s[0:1], -1
	v_pk_mul_f32 v[96:97], v[100:101], v[96:97]
	s_nop 0
	v_cvt_pk_bf16_f32 v106, v96, v97
	v_pk_mul_f32 v[96:97], v[102:103], v[108:109]
	s_nop 0
	v_pk_mul_f32 v[96:97], v[96:97], v[98:99]
	v_mul_f32_e32 v98, 0xbfb8aa3b, v92
	v_mul_f32_e32 v99, 0xbfb8aa3b, v93
	v_exp_f32_e32 v98, v98
	v_exp_f32_e32 v99, v99
	v_cvt_pk_bf16_f32 v107, v96, v97
	v_lshl_add_u64 v[96:97], v[162:163], 0, v[140:141]
	global_store_dwordx4 v[96:97], v[104:107], off
	v_add_f32_e32 v96, 1.0, v98
	v_add_f32_e32 v97, 1.0, v99
	v_mul_f32_e32 v98, 0xbfb8aa3b, v94
	v_mul_f32_e32 v99, 0xbfb8aa3b, v95
	v_exp_f32_e32 v98, v98
	v_exp_f32_e32 v99, v99
	v_rcp_f32_e32 v96, v96
	v_rcp_f32_e32 v97, v97
	v_add_f32_e32 v98, 1.0, v98
	v_add_f32_e32 v99, 1.0, v99
	v_rcp_f32_e32 v98, v98
	v_rcp_f32_e32 v99, v99
	v_pk_mul_f32 v[92:93], v[92:93], v[96:97]
	s_nop 0
	v_pk_mul_f32 v[88:89], v[92:93], v[88:89]
	v_pk_mul_f32 v[92:93], v[94:95], v[98:99]
	v_cvt_pk_bf16_f32 v88, v88, v89
	v_mul_f32_e32 v89, 0xbfb8aa3b, v84
	v_pk_mul_f32 v[90:91], v[92:93], v[90:91]
	v_exp_f32_e32 v92, v89
	v_mul_f32_e32 v89, 0xbfb8aa3b, v85
	v_exp_f32_e32 v93, v89
	v_cvt_pk_bf16_f32 v89, v90, v91
	v_add_f32_e32 v90, 1.0, v92
	v_mul_f32_e32 v92, 0xbfb8aa3b, v86
	v_add_f32_e32 v91, 1.0, v93
	v_mul_f32_e32 v93, 0xbfb8aa3b, v87
	v_exp_f32_e32 v92, v92
	v_exp_f32_e32 v93, v93
	v_rcp_f32_e32 v90, v90
	v_rcp_f32_e32 v91, v91
	v_add_f32_e32 v92, 1.0, v92
	v_add_f32_e32 v93, 1.0, v93
	v_rcp_f32_e32 v92, v92
	v_rcp_f32_e32 v93, v93
	v_pk_mul_f32 v[84:85], v[84:85], v[90:91]
	s_nop 0
	v_pk_mul_f32 v[80:81], v[84:85], v[80:81]
	s_nop 0
	v_cvt_pk_bf16_f32 v90, v80, v81
	v_pk_mul_f32 v[80:81], v[86:87], v[92:93]
	s_nop 0
	v_pk_mul_f32 v[80:81], v[80:81], v[82:83]
	v_mul_f32_e32 v82, 0xbfb8aa3b, v76
	v_mul_f32_e32 v83, 0xbfb8aa3b, v77
	v_exp_f32_e32 v82, v82
	v_exp_f32_e32 v83, v83
	v_cvt_pk_bf16_f32 v91, v80, v81
	v_lshl_add_u64 v[80:81], v[162:163], 0, v[142:143]
	global_store_dwordx4 v[80:81], v[88:91], off
	v_add_f32_e32 v80, 1.0, v82
	v_add_f32_e32 v81, 1.0, v83
	v_mul_f32_e32 v82, 0xbfb8aa3b, v78
	v_mul_f32_e32 v83, 0xbfb8aa3b, v79
	v_exp_f32_e32 v82, v82
	v_exp_f32_e32 v83, v83
	v_rcp_f32_e32 v80, v80
	v_rcp_f32_e32 v81, v81
	v_add_f32_e32 v82, 1.0, v82
	v_add_f32_e32 v83, 1.0, v83
	v_rcp_f32_e32 v82, v82
	v_rcp_f32_e32 v83, v83
	v_pk_mul_f32 v[76:77], v[76:77], v[80:81]
	s_nop 0
	v_pk_mul_f32 v[72:73], v[76:77], v[72:73]
	v_pk_mul_f32 v[76:77], v[78:79], v[82:83]
	v_cvt_pk_bf16_f32 v72, v72, v73
	v_mul_f32_e32 v73, 0xbfb8aa3b, v68
	v_pk_mul_f32 v[74:75], v[76:77], v[74:75]
	v_exp_f32_e32 v76, v73
	v_mul_f32_e32 v73, 0xbfb8aa3b, v69
	v_exp_f32_e32 v77, v73
	v_cvt_pk_bf16_f32 v73, v74, v75
	v_add_f32_e32 v74, 1.0, v76
	v_mul_f32_e32 v76, 0xbfb8aa3b, v70
	v_add_f32_e32 v75, 1.0, v77
	v_mul_f32_e32 v77, 0xbfb8aa3b, v71
	v_exp_f32_e32 v76, v76
	v_exp_f32_e32 v77, v77
	v_rcp_f32_e32 v74, v74
	v_rcp_f32_e32 v75, v75
	v_add_f32_e32 v76, 1.0, v76
	v_add_f32_e32 v77, 1.0, v77
	v_rcp_f32_e32 v76, v76
	v_rcp_f32_e32 v77, v77
	v_pk_mul_f32 v[68:69], v[68:69], v[74:75]
	s_nop 0
	v_pk_mul_f32 v[64:65], v[68:69], v[64:65]
	s_nop 0
	v_cvt_pk_bf16_f32 v74, v64, v65
	v_pk_mul_f32 v[64:65], v[70:71], v[76:77]
	s_nop 0
	v_pk_mul_f32 v[64:65], v[64:65], v[66:67]
	v_mul_f32_e32 v66, 0xbfb8aa3b, v60
	v_mul_f32_e32 v67, 0xbfb8aa3b, v61
	v_exp_f32_e32 v66, v66
	v_exp_f32_e32 v67, v67
	v_cvt_pk_bf16_f32 v75, v64, v65
	v_lshl_add_u64 v[64:65], v[162:163], 0, v[144:145]
	global_store_dwordx4 v[64:65], v[72:75], off
	s_cmp_lg_u32 s54, 0
	s_cbranch_scc1 .Lts0_epi_end
	v_add_f32_e32 v64, 1.0, v66
	v_add_f32_e32 v65, 1.0, v67
	v_mul_f32_e32 v66, 0xbfb8aa3b, v62
	v_mul_f32_e32 v67, 0xbfb8aa3b, v63
	v_exp_f32_e32 v66, v66
	v_exp_f32_e32 v67, v67
	v_rcp_f32_e32 v64, v64
	v_rcp_f32_e32 v65, v65
	v_add_f32_e32 v66, 1.0, v66
	v_add_f32_e32 v67, 1.0, v67
	v_rcp_f32_e32 v66, v66
	v_rcp_f32_e32 v67, v67
	v_pk_mul_f32 v[60:61], v[60:61], v[64:65]
	s_nop 0
	v_pk_mul_f32 v[56:57], v[60:61], v[56:57]
	v_pk_mul_f32 v[60:61], v[62:63], v[66:67]
	v_cvt_pk_bf16_f32 v56, v56, v57
	v_mul_f32_e32 v57, 0xbfb8aa3b, v52
	v_pk_mul_f32 v[58:59], v[60:61], v[58:59]
	v_exp_f32_e32 v60, v57
	v_mul_f32_e32 v57, 0xbfb8aa3b, v53
	v_exp_f32_e32 v61, v57
	v_cvt_pk_bf16_f32 v57, v58, v59
	v_add_f32_e32 v58, 1.0, v60
	v_mul_f32_e32 v60, 0xbfb8aa3b, v54
	v_add_f32_e32 v59, 1.0, v61
	v_mul_f32_e32 v61, 0xbfb8aa3b, v55
	v_exp_f32_e32 v60, v60
	v_exp_f32_e32 v61, v61
	v_rcp_f32_e32 v58, v58
	v_rcp_f32_e32 v59, v59
	v_add_f32_e32 v60, 1.0, v60
	v_add_f32_e32 v61, 1.0, v61
	v_rcp_f32_e32 v60, v60
	v_rcp_f32_e32 v61, v61
	v_pk_mul_f32 v[52:53], v[52:53], v[58:59]
	s_nop 0
	v_pk_mul_f32 v[48:49], v[52:53], v[48:49]
	s_nop 0
	v_cvt_pk_bf16_f32 v58, v48, v49
	v_pk_mul_f32 v[48:49], v[54:55], v[60:61]
	s_nop 0
	v_pk_mul_f32 v[48:49], v[48:49], v[50:51]
	v_mul_f32_e32 v50, 0xbfb8aa3b, v44
	v_mul_f32_e32 v51, 0xbfb8aa3b, v45
	v_exp_f32_e32 v50, v50
	v_exp_f32_e32 v51, v51
	v_cvt_pk_bf16_f32 v59, v48, v49
	v_lshl_add_u64 v[48:49], v[162:163], 0, v[146:147]
	global_store_dwordx4 v[48:49], v[56:59], off
	v_add_f32_e32 v48, 1.0, v50
	v_add_f32_e32 v49, 1.0, v51
	v_mul_f32_e32 v50, 0xbfb8aa3b, v46
	v_mul_f32_e32 v51, 0xbfb8aa3b, v47
	v_exp_f32_e32 v50, v50
	v_exp_f32_e32 v51, v51
	v_rcp_f32_e32 v48, v48
	v_rcp_f32_e32 v49, v49
	v_add_f32_e32 v50, 1.0, v50
	v_add_f32_e32 v51, 1.0, v51
	v_rcp_f32_e32 v50, v50
	v_rcp_f32_e32 v51, v51
	v_pk_mul_f32 v[44:45], v[44:45], v[48:49]
	s_nop 0
	v_pk_mul_f32 v[40:41], v[44:45], v[40:41]
	v_pk_mul_f32 v[44:45], v[46:47], v[50:51]
	v_cvt_pk_bf16_f32 v40, v40, v41
	v_mul_f32_e32 v41, 0xbfb8aa3b, v36
	v_pk_mul_f32 v[42:43], v[44:45], v[42:43]
	v_exp_f32_e32 v44, v41
	v_mul_f32_e32 v41, 0xbfb8aa3b, v37
	v_exp_f32_e32 v45, v41
	v_cvt_pk_bf16_f32 v41, v42, v43
	v_add_f32_e32 v42, 1.0, v44
	v_mul_f32_e32 v44, 0xbfb8aa3b, v38
	v_add_f32_e32 v43, 1.0, v45
	v_mul_f32_e32 v45, 0xbfb8aa3b, v39
	v_exp_f32_e32 v44, v44
	v_exp_f32_e32 v45, v45
	v_rcp_f32_e32 v42, v42
	v_rcp_f32_e32 v43, v43
	v_add_f32_e32 v44, 1.0, v44
	v_add_f32_e32 v45, 1.0, v45
	v_rcp_f32_e32 v44, v44
	v_rcp_f32_e32 v45, v45
	v_pk_mul_f32 v[36:37], v[36:37], v[42:43]
	s_nop 0
	v_pk_mul_f32 v[32:33], v[36:37], v[32:33]
	s_nop 0
	v_cvt_pk_bf16_f32 v42, v32, v33
	v_pk_mul_f32 v[32:33], v[38:39], v[44:45]
	s_nop 0
	v_pk_mul_f32 v[32:33], v[32:33], v[34:35]
	v_mul_f32_e32 v34, 0xbfb8aa3b, v28
	v_mul_f32_e32 v35, 0xbfb8aa3b, v29
	v_exp_f32_e32 v34, v34
	v_exp_f32_e32 v35, v35
	v_cvt_pk_bf16_f32 v43, v32, v33
	v_lshl_add_u64 v[32:33], v[162:163], 0, v[148:149]
	global_store_dwordx4 v[32:33], v[40:43], off
	v_add_f32_e32 v32, 1.0, v34
	v_add_f32_e32 v33, 1.0, v35
	v_mul_f32_e32 v34, 0xbfb8aa3b, v30
	v_mul_f32_e32 v35, 0xbfb8aa3b, v31
	v_exp_f32_e32 v34, v34
	v_exp_f32_e32 v35, v35
	v_rcp_f32_e32 v32, v32
	v_rcp_f32_e32 v33, v33
	v_add_f32_e32 v34, 1.0, v34
	v_add_f32_e32 v35, 1.0, v35
	v_rcp_f32_e32 v34, v34
	v_rcp_f32_e32 v35, v35
	v_pk_mul_f32 v[28:29], v[28:29], v[32:33]
	s_nop 0
	v_pk_mul_f32 v[24:25], v[28:29], v[24:25]
	v_pk_mul_f32 v[28:29], v[30:31], v[34:35]
	v_cvt_pk_bf16_f32 v24, v24, v25
	v_mul_f32_e32 v25, 0xbfb8aa3b, v20
	v_pk_mul_f32 v[26:27], v[28:29], v[26:27]
	v_exp_f32_e32 v28, v25
	v_mul_f32_e32 v25, 0xbfb8aa3b, v21
	v_exp_f32_e32 v29, v25
	v_cvt_pk_bf16_f32 v25, v26, v27
	v_add_f32_e32 v26, 1.0, v28
	v_mul_f32_e32 v28, 0xbfb8aa3b, v22
	v_add_f32_e32 v27, 1.0, v29
	v_mul_f32_e32 v29, 0xbfb8aa3b, v23
	v_exp_f32_e32 v28, v28
	v_exp_f32_e32 v29, v29
	v_rcp_f32_e32 v26, v26
	v_rcp_f32_e32 v27, v27
	v_add_f32_e32 v28, 1.0, v28
	v_add_f32_e32 v29, 1.0, v29
	v_rcp_f32_e32 v28, v28
	v_rcp_f32_e32 v29, v29
	v_pk_mul_f32 v[20:21], v[20:21], v[26:27]
	s_nop 0
	v_pk_mul_f32 v[16:17], v[20:21], v[16:17]
	s_nop 0
	v_cvt_pk_bf16_f32 v26, v16, v17
	v_pk_mul_f32 v[16:17], v[22:23], v[28:29]
	s_nop 0
	v_pk_mul_f32 v[16:17], v[16:17], v[18:19]
	v_mul_f32_e32 v18, 0xbfb8aa3b, v12
	v_mul_f32_e32 v19, 0xbfb8aa3b, v13
	v_exp_f32_e32 v18, v18
	v_exp_f32_e32 v19, v19
	v_cvt_pk_bf16_f32 v27, v16, v17
	v_lshl_add_u64 v[16:17], v[162:163], 0, v[150:151]
	global_store_dwordx4 v[16:17], v[24:27], off
	v_add_f32_e32 v16, 1.0, v18
	v_add_f32_e32 v17, 1.0, v19
	v_mul_f32_e32 v18, 0xbfb8aa3b, v14
	v_mul_f32_e32 v19, 0xbfb8aa3b, v15
	v_exp_f32_e32 v18, v18
	v_exp_f32_e32 v19, v19
	v_rcp_f32_e32 v16, v16
	v_rcp_f32_e32 v17, v17
	v_add_f32_e32 v18, 1.0, v18
	v_add_f32_e32 v19, 1.0, v19
	v_rcp_f32_e32 v18, v18
	v_rcp_f32_e32 v19, v19
	v_pk_mul_f32 v[12:13], v[12:13], v[16:17]
	s_nop 0
	v_pk_mul_f32 v[8:9], v[12:13], v[8:9]
	v_pk_mul_f32 v[12:13], v[14:15], v[18:19]
	v_cvt_pk_bf16_f32 v8, v8, v9
	v_mul_f32_e32 v9, 0xbfb8aa3b, v4
	v_pk_mul_f32 v[10:11], v[12:13], v[10:11]
	v_exp_f32_e32 v12, v9
	v_mul_f32_e32 v9, 0xbfb8aa3b, v5
	v_exp_f32_e32 v13, v9
	v_cvt_pk_bf16_f32 v9, v10, v11
	v_add_f32_e32 v10, 1.0, v12
	v_mul_f32_e32 v12, 0xbfb8aa3b, v6
	v_add_f32_e32 v11, 1.0, v13
	v_mul_f32_e32 v13, 0xbfb8aa3b, v7
	v_exp_f32_e32 v12, v12
	v_exp_f32_e32 v13, v13
	v_rcp_f32_e32 v10, v10
	v_rcp_f32_e32 v11, v11
	v_add_f32_e32 v12, 1.0, v12
	v_add_f32_e32 v13, 1.0, v13
	v_rcp_f32_e32 v12, v12
	v_rcp_f32_e32 v13, v13
	v_pk_mul_f32 v[4:5], v[4:5], v[10:11]
	s_nop 0
	v_pk_mul_f32 v[0:1], v[4:5], v[0:1]
	s_nop 0
	v_cvt_pk_bf16_f32 v10, v0, v1
	v_pk_mul_f32 v[0:1], v[6:7], v[12:13]
	s_nop 0
	v_pk_mul_f32 v[0:1], v[0:1], v[2:3]
	s_nop 0
	v_cvt_pk_bf16_f32 v11, v0, v1
	v_lshl_add_u64 v[0:1], v[162:163], 0, v[152:153]
	global_store_dwordx4 v[0:1], v[8:11], off
.Lts0_epi_end:
	s_cbranch_vccnz .LBB0_1559
	s_andn2_b64 vcc, exec, s[2:3]
	s_cbranch_vccnz .LBB0_1558
	s_barrier
	s_branch .LBB0_1558
